# v046 with s_sleep 1 removed from the grid-barrier polling loops (spin latency)
# baseline (speedup 1.0000x reference)
; __global__ void __launch_bounds__(512, 2) mk_fwd(Params p) {
;     ...
;     if (p.coop) cg::this_grid().sync();
.LBB0_9:
	global_load_dword v3, v1, s[4:5] offset:32 sc1
	s_waitcnt vmcnt(0)
	v_and_b32_e32 v3, 0xffff0000, v3
	v_cmp_ne_u32_e32 vcc, v3, v0
	s_or_b64 s[6:7], vcc, s[6:7]
	s_andn2_b64 exec, exec, s[6:7]
	s_cbranch_execnz .LBB0_9

; __device__ __forceinline__ unsigned xb_ld(unsigned* p)              { return __hip_atomic_load(p, __ATOMIC_RELAXED, __HIP_MEMORY_SCOPE_AGENT); }
; __device__ __forceinline__ void xcd_barrier_complete(unsigned* bar, unsigned x, unsigned& nloc, unsigned& nx) {
;     const unsigned G = gridDim.x * gridDim.y * gridDim.z;
;     unsigned sum, cnt, mine, sp = 0u;
;     for (;;) {
;         sum = 0u; cnt = 0u; mine = 0u;
; #pragma unroll
;         for (unsigned j = 0; j < 16; ++j) { const unsigned c = xb_ld(&bar[XB_XCNT(j)]); sum += c; cnt += (c > 0u) ? 1u : 0u; mine = (j == x) ? c : mine; }
;         if (sum == G) break;
;         __builtin_amdgcn_s_sleep(1);
;         if ((++sp & 255u) == 0u) { if (xb_ld(&bar[XB_TMO])) break; if (sp > XB_SPIN_CAP) { atomicAdd(&bar[XB_TMO], 1u); break; } }
;     }
;     nloc = mine > 0u ? mine : 1u; nx = cnt > 0u ? cnt : 1u;
; }
.LBB0_65:
	flat_load_dword v47, v[0:1] sc1
	flat_load_dword v32, v[2:3] sc1
	flat_load_dword v33, v[4:5] sc1
	flat_load_dword v34, v[6:7] sc1
	flat_load_dword v35, v[8:9] sc1
	flat_load_dword v36, v[10:11] sc1
	flat_load_dword v37, v[12:13] sc1
	flat_load_dword v38, v[14:15] sc1
	flat_load_dword v39, v[16:17] sc1
	flat_load_dword v40, v[18:19] sc1
	flat_load_dword v41, v[20:21] sc1
	flat_load_dword v42, v[22:23] sc1
	flat_load_dword v43, v[24:25] sc1
	flat_load_dword v44, v[26:27] sc1
	flat_load_dword v45, v[28:29] sc1
	flat_load_dword v46, v[30:31] sc1
	s_or_b64 s[10:11], s[10:11], exec
	s_or_b64 s[8:9], s[8:9], exec
	s_waitcnt vmcnt(0) lgkmcnt(0)
	v_add_u32_e32 v48, v32, v47
	v_add_u32_e32 v48, v48, v33
	v_add_u32_e32 v48, v48, v34
	v_add_u32_e32 v48, v48, v35
	v_add_u32_e32 v48, v48, v36
	v_add_u32_e32 v48, v48, v37
	v_add_u32_e32 v48, v48, v38
	v_add_u32_e32 v48, v48, v39
	v_add_u32_e32 v48, v48, v40
	v_add_u32_e32 v48, v48, v41
	v_add_u32_e32 v48, v48, v42
	v_add_u32_e32 v48, v48, v43
	v_add_u32_e32 v48, v48, v44
	v_add_u32_e32 v48, v48, v45
	v_add_u32_e32 v48, v48, v46
	v_cmp_ne_u32_e32 vcc, s24, v48
	s_and_saveexec_b64 s[12:13], vcc
	s_cbranch_execz .LBB0_64
	s_and_b32 s16, s25, 0xff
	s_mov_b64 s[14:15], -1
	s_cmp_eq_u32 s16, 0
	s_mov_b64 s[18:19], -1
	s_mov_b64 s[16:17], -1
	s_cbranch_scc1 .LBB0_68
	s_and_saveexec_b64 s[20:21], s[18:19]
	s_cbranch_execz .LBB0_63
	s_branch .LBB0_71

; __device__ __forceinline__ unsigned xb_ld(unsigned* p)              { return __hip_atomic_load(p, __ATOMIC_RELAXED, __HIP_MEMORY_SCOPE_AGENT); }
; __device__ __forceinline__ unsigned xb_add(unsigned* p, unsigned v) { return __hip_atomic_fetch_add(p, v, __ATOMIC_RELAXED, __HIP_MEMORY_SCOPE_AGENT); }
; #define XB_SPIN(cond, bar) do { unsigned _sp = 0; while (cond) { __builtin_amdgcn_s_sleep(1); \
;     if ((++_sp & 255u) == 0u) { if (xb_ld(&(bar)[XB_TMO])) break; if (_sp > XB_SPIN_CAP) { atomicAdd(&(bar)[XB_TMO], 1u); break; } } } } while (0)
; __device__ __forceinline__ void grid_barrier(unsigned* bar, volatile LAS unsigned* st, int wid) {
;     ...
;                 const unsigned tg = og / nx;
;                 if (og + 1u == (tg + 1u) * nx) xb_add(&bar[XB_TOPGEN], 1u);
;                 else XB_SPIN(xb_ld(&bar[XB_TOPGEN]) == tg, bar);
;                 __builtin_amdgcn_fence(__ATOMIC_ACQUIRE, "agent");
;                 xb_add(&bar[XB_XGEN(x)], 1u);
;                 asm volatile("s_waitcnt vmcnt(0)" ::: "memory");
;             } else {
;                 XB_SPIN(xb_ld(&bar[XB_XGEN(x)]) == gen, bar);
;                 __builtin_amdgcn_fence(__ATOMIC_ACQUIRE, "agent");
;                 asm volatile("s_waitcnt vmcnt(0)" ::: "memory");
;             }
.LBB0_79:
	s_and_b32 s18, s27, 0xff
	s_mov_b64 s[16:17], -1
	s_cmp_lg_u32 s18, 0
	s_mov_b64 s[18:19], -1
	s_cbranch_scc1 .LBB0_83
	v_mov_b64_e32 v[2:3], s[6:7]
	flat_load_dword v0, v[2:3] sc1
	s_mov_b64 s[18:19], 0
	s_mov_b64 s[20:21], -1
	s_waitcnt vmcnt(0) lgkmcnt(0)
	v_cmp_eq_u32_e32 vcc, 0, v0
	s_and_saveexec_b64 s[24:25], vcc
	s_cmp_lt_u32 s27, 0x100001
	s_cselect_b64 s[18:19], -1, 0
	s_xor_b64 s[20:21], exec, -1
	s_and_b64 s[18:19], s[18:19], exec
	s_or_b64 exec, exec, s[24:25]

; __device__ __forceinline__ unsigned xb_ld(unsigned* p)              { return __hip_atomic_load(p, __ATOMIC_RELAXED, __HIP_MEMORY_SCOPE_AGENT); }
; __device__ __forceinline__ unsigned xb_add(unsigned* p, unsigned v) { return __hip_atomic_fetch_add(p, v, __ATOMIC_RELAXED, __HIP_MEMORY_SCOPE_AGENT); }
; #define XB_SPIN(cond, bar) do { unsigned _sp = 0; while (cond) { __builtin_amdgcn_s_sleep(1); \
;     if ((++_sp & 255u) == 0u) { if (xb_ld(&(bar)[XB_TMO])) break; if (_sp > XB_SPIN_CAP) { atomicAdd(&(bar)[XB_TMO], 1u); break; } } } } while (0)
; __device__ __forceinline__ void grid_barrier(unsigned* bar, volatile LAS unsigned* st, int wid) {
;     ...
;                 const unsigned tg = og / nx;
;                 if (og + 1u == (tg + 1u) * nx) xb_add(&bar[XB_TOPGEN], 1u);
;                 else XB_SPIN(xb_ld(&bar[XB_TOPGEN]) == tg, bar);
;                 __builtin_amdgcn_fence(__ATOMIC_ACQUIRE, "agent");
;                 xb_add(&bar[XB_XGEN(x)], 1u);
;                 asm volatile("s_waitcnt vmcnt(0)" ::: "memory");
;             } else {
;                 XB_SPIN(xb_ld(&bar[XB_XGEN(x)]) == gen, bar);
;                 __builtin_amdgcn_fence(__ATOMIC_ACQUIRE, "agent");
;                 asm volatile("s_waitcnt vmcnt(0)" ::: "memory");
;             }
.LBB0_93:
	s_and_b32 s14, s24, 0xff
	s_cmp_lg_u32 s14, 0
	s_mov_b64 s[16:17], -1
	s_cbranch_scc1 .LBB0_97
	v_mov_b64_e32 v[0:1], s[6:7]
	flat_load_dword v0, v[0:1] sc1
	s_mov_b64 s[16:17], 0
	s_mov_b64 s[14:15], -1
	s_waitcnt vmcnt(0) lgkmcnt(0)
	v_cmp_eq_u32_e32 vcc, 0, v0
	s_and_saveexec_b64 s[18:19], vcc
	s_cmp_lt_u32 s24, 0x100001
	s_cselect_b64 s[16:17], -1, 0
	s_xor_b64 s[14:15], exec, -1
	s_and_b64 s[16:17], s[16:17], exec
	s_or_b64 exec, exec, s[18:19]

; __device__ __forceinline__ unsigned xb_ld(unsigned* p)              { return __hip_atomic_load(p, __ATOMIC_RELAXED, __HIP_MEMORY_SCOPE_AGENT); }
; __device__ __forceinline__ void xcd_barrier_complete(unsigned* bar, unsigned x, unsigned& nloc, unsigned& nx) {
;     const unsigned G = gridDim.x * gridDim.y * gridDim.z;
;     unsigned sum, cnt, mine, sp = 0u;
;     for (;;) {
;         sum = 0u; cnt = 0u; mine = 0u;
; #pragma unroll
;         for (unsigned j = 0; j < 16; ++j) { const unsigned c = xb_ld(&bar[XB_XCNT(j)]); sum += c; cnt += (c > 0u) ? 1u : 0u; mine = (j == x) ? c : mine; }
;         if (sum == G) break;
;         __builtin_amdgcn_s_sleep(1);
;         if ((++sp & 255u) == 0u) { if (xb_ld(&bar[XB_TMO])) break; if (sp > XB_SPIN_CAP) { atomicAdd(&bar[XB_TMO], 1u); break; } }
;     }
;     nloc = mine > 0u ? mine : 1u; nx = cnt > 0u ? cnt : 1u;
; }
.LBB0_201:
	flat_load_dword v47, v[0:1] sc1
	flat_load_dword v32, v[2:3] sc1
	flat_load_dword v33, v[4:5] sc1
	flat_load_dword v34, v[6:7] sc1
	flat_load_dword v35, v[8:9] sc1
	flat_load_dword v36, v[10:11] sc1
	flat_load_dword v37, v[12:13] sc1
	flat_load_dword v38, v[14:15] sc1
	flat_load_dword v39, v[16:17] sc1
	flat_load_dword v40, v[18:19] sc1
	flat_load_dword v41, v[20:21] sc1
	flat_load_dword v42, v[22:23] sc1
	flat_load_dword v43, v[24:25] sc1
	flat_load_dword v44, v[26:27] sc1
	flat_load_dword v45, v[28:29] sc1
	flat_load_dword v46, v[30:31] sc1
	s_or_b64 s[10:11], s[10:11], exec
	s_or_b64 s[8:9], s[8:9], exec
	s_waitcnt vmcnt(0) lgkmcnt(0)
	v_add_u32_e32 v48, v32, v47
	v_add_u32_e32 v48, v48, v33
	v_add_u32_e32 v48, v48, v34
	v_add_u32_e32 v48, v48, v35
	v_add_u32_e32 v48, v48, v36
	v_add_u32_e32 v48, v48, v37
	v_add_u32_e32 v48, v48, v38
	v_add_u32_e32 v48, v48, v39
	v_add_u32_e32 v48, v48, v40
	v_add_u32_e32 v48, v48, v41
	v_add_u32_e32 v48, v48, v42
	v_add_u32_e32 v48, v48, v43
	v_add_u32_e32 v48, v48, v44
	v_add_u32_e32 v48, v48, v45
	v_add_u32_e32 v48, v48, v46
	v_cmp_ne_u32_e32 vcc, s24, v48
	s_and_saveexec_b64 s[12:13], vcc
	s_cbranch_execz .LBB0_200
	s_and_b32 s16, s25, 0xff
	s_mov_b64 s[14:15], -1
	s_cmp_eq_u32 s16, 0
	s_mov_b64 s[18:19], -1
	s_mov_b64 s[16:17], -1
	s_cbranch_scc0 .LBB0_206
	v_mov_b64_e32 v[48:49], s[2:3]
	flat_load_dword v48, v[48:49] sc1
	s_mov_b64 s[18:19], 0
	s_waitcnt vmcnt(0) lgkmcnt(0)
	v_cmp_eq_u32_e32 vcc, 0, v48
	s_and_saveexec_b64 s[20:21], vcc
	s_cmp_lt_u32 s25, 0x100001
	s_cselect_b64 s[18:19], -1, 0
	s_xor_b64 s[16:17], exec, -1
	s_and_b64 s[18:19], s[18:19], exec
	s_or_b64 exec, exec, s[20:21]

; __device__ __forceinline__ unsigned xb_ld(unsigned* p)              { return __hip_atomic_load(p, __ATOMIC_RELAXED, __HIP_MEMORY_SCOPE_AGENT); }
; __device__ __forceinline__ unsigned xb_add(unsigned* p, unsigned v) { return __hip_atomic_fetch_add(p, v, __ATOMIC_RELAXED, __HIP_MEMORY_SCOPE_AGENT); }
; #define XB_SPIN(cond, bar) do { unsigned _sp = 0; while (cond) { __builtin_amdgcn_s_sleep(1); \
;     if ((++_sp & 255u) == 0u) { if (xb_ld(&(bar)[XB_TMO])) break; if (_sp > XB_SPIN_CAP) { atomicAdd(&(bar)[XB_TMO], 1u); break; } } } } while (0)
; __device__ __forceinline__ void grid_barrier(unsigned* bar, volatile LAS unsigned* st, int wid) {
;     ...
;                 const unsigned tg = og / nx;
;                 if (og + 1u == (tg + 1u) * nx) xb_add(&bar[XB_TOPGEN], 1u);
;                 else XB_SPIN(xb_ld(&bar[XB_TOPGEN]) == tg, bar);
;                 __builtin_amdgcn_fence(__ATOMIC_ACQUIRE, "agent");
;                 xb_add(&bar[XB_XGEN(x)], 1u);
;                 asm volatile("s_waitcnt vmcnt(0)" ::: "memory");
;             } else {
;                 XB_SPIN(xb_ld(&bar[XB_XGEN(x)]) == gen, bar);
;                 __builtin_amdgcn_fence(__ATOMIC_ACQUIRE, "agent");
;                 asm volatile("s_waitcnt vmcnt(0)" ::: "memory");
;             }
.LBB0_215:
	s_and_b32 s18, s28, 0xff
	s_mov_b64 s[16:17], -1
	s_cmp_lg_u32 s18, 0
	s_mov_b64 s[18:19], -1
	s_cbranch_scc1 .LBB0_219
	v_mov_b64_e32 v[2:3], s[6:7]
	flat_load_dword v0, v[2:3] sc1
	s_mov_b64 s[18:19], 0
	s_mov_b64 s[20:21], -1
	s_waitcnt vmcnt(0) lgkmcnt(0)
	v_cmp_eq_u32_e32 vcc, 0, v0
	s_and_saveexec_b64 s[24:25], vcc
	s_cmp_lt_u32 s28, 0x100001
	s_cselect_b64 s[18:19], -1, 0
	s_xor_b64 s[20:21], exec, -1
	s_and_b64 s[18:19], s[18:19], exec
	s_or_b64 exec, exec, s[24:25]

; __device__ __forceinline__ unsigned xb_ld(unsigned* p)              { return __hip_atomic_load(p, __ATOMIC_RELAXED, __HIP_MEMORY_SCOPE_AGENT); }
; __device__ __forceinline__ unsigned xb_add(unsigned* p, unsigned v) { return __hip_atomic_fetch_add(p, v, __ATOMIC_RELAXED, __HIP_MEMORY_SCOPE_AGENT); }
; #define XB_SPIN(cond, bar) do { unsigned _sp = 0; while (cond) { __builtin_amdgcn_s_sleep(1); \
;     if ((++_sp & 255u) == 0u) { if (xb_ld(&(bar)[XB_TMO])) break; if (_sp > XB_SPIN_CAP) { atomicAdd(&(bar)[XB_TMO], 1u); break; } } } } while (0)
; __device__ __forceinline__ void grid_barrier(unsigned* bar, volatile LAS unsigned* st, int wid) {
;     ...
;                 const unsigned tg = og / nx;
;                 if (og + 1u == (tg + 1u) * nx) xb_add(&bar[XB_TOPGEN], 1u);
;                 else XB_SPIN(xb_ld(&bar[XB_TOPGEN]) == tg, bar);
;                 __builtin_amdgcn_fence(__ATOMIC_ACQUIRE, "agent");
;                 xb_add(&bar[XB_XGEN(x)], 1u);
;                 asm volatile("s_waitcnt vmcnt(0)" ::: "memory");
;             } else {
;                 XB_SPIN(xb_ld(&bar[XB_XGEN(x)]) == gen, bar);
;                 __builtin_amdgcn_fence(__ATOMIC_ACQUIRE, "agent");
;                 asm volatile("s_waitcnt vmcnt(0)" ::: "memory");
;             }
.LBB0_229:
	s_and_b32 s14, s23, 0xff
	s_cmp_lg_u32 s14, 0
	s_mov_b64 s[16:17], -1
	s_cbranch_scc1 .LBB0_233
	v_mov_b64_e32 v[0:1], s[6:7]
	flat_load_dword v0, v[0:1] sc1
	s_mov_b64 s[16:17], 0
	s_mov_b64 s[14:15], -1
	s_waitcnt vmcnt(0) lgkmcnt(0)
	v_cmp_eq_u32_e32 vcc, 0, v0
	s_and_saveexec_b64 s[18:19], vcc
	s_cmp_lt_u32 s23, 0x100001
	s_cselect_b64 s[16:17], -1, 0
	s_xor_b64 s[14:15], exec, -1
	s_and_b64 s[16:17], s[16:17], exec
	s_or_b64 exec, exec, s[18:19]

; __device__ __forceinline__ unsigned xb_ld(unsigned* p)              { return __hip_atomic_load(p, __ATOMIC_RELAXED, __HIP_MEMORY_SCOPE_AGENT); }
; __device__ __forceinline__ void xcd_barrier_complete(unsigned* bar, unsigned x, unsigned& nloc, unsigned& nx) {
;     const unsigned G = gridDim.x * gridDim.y * gridDim.z;
;     unsigned sum, cnt, mine, sp = 0u;
;     for (;;) {
;         sum = 0u; cnt = 0u; mine = 0u;
; #pragma unroll
;         for (unsigned j = 0; j < 16; ++j) { const unsigned c = xb_ld(&bar[XB_XCNT(j)]); sum += c; cnt += (c > 0u) ? 1u : 0u; mine = (j == x) ? c : mine; }
;         if (sum == G) break;
;         __builtin_amdgcn_s_sleep(1);
;         if ((++sp & 255u) == 0u) { if (xb_ld(&bar[XB_TMO])) break; if (sp > XB_SPIN_CAP) { atomicAdd(&bar[XB_TMO], 1u); break; } }
;     }
;     nloc = mine > 0u ? mine : 1u; nx = cnt > 0u ? cnt : 1u;
; }
.LBB0_1065:
	flat_load_dword v47, v[0:1] sc1
	flat_load_dword v32, v[2:3] sc1
	flat_load_dword v33, v[4:5] sc1
	flat_load_dword v34, v[6:7] sc1
	flat_load_dword v35, v[8:9] sc1
	flat_load_dword v36, v[10:11] sc1
	flat_load_dword v37, v[12:13] sc1
	flat_load_dword v38, v[14:15] sc1
	flat_load_dword v39, v[16:17] sc1
	flat_load_dword v40, v[18:19] sc1
	flat_load_dword v41, v[20:21] sc1
	flat_load_dword v42, v[22:23] sc1
	flat_load_dword v43, v[24:25] sc1
	flat_load_dword v44, v[26:27] sc1
	flat_load_dword v45, v[28:29] sc1
	flat_load_dword v46, v[30:31] sc1
	s_or_b64 s[10:11], s[10:11], exec
	s_or_b64 s[8:9], s[8:9], exec
	s_waitcnt vmcnt(0) lgkmcnt(0)
	v_add_u32_e32 v48, v32, v47
	v_add_u32_e32 v48, v48, v33
	v_add_u32_e32 v48, v48, v34
	v_add_u32_e32 v48, v48, v35
	v_add_u32_e32 v48, v48, v36
	v_add_u32_e32 v48, v48, v37
	v_add_u32_e32 v48, v48, v38
	v_add_u32_e32 v48, v48, v39
	v_add_u32_e32 v48, v48, v40
	v_add_u32_e32 v48, v48, v41
	v_add_u32_e32 v48, v48, v42
	v_add_u32_e32 v48, v48, v43
	v_add_u32_e32 v48, v48, v44
	v_add_u32_e32 v48, v48, v45
	v_add_u32_e32 v48, v48, v46
	v_cmp_ne_u32_e32 vcc, s24, v48
	s_and_saveexec_b64 s[12:13], vcc
	s_cbranch_execz .LBB0_1064
	s_and_b32 s0, s25, 0xff
	s_mov_b64 s[14:15], -1
	s_cmp_eq_u32 s0, 0
	s_mov_b64 s[18:19], -1
	s_mov_b64 s[16:17], -1
	s_cbranch_scc0 .LBB0_1070
	v_mov_b64_e32 v[48:49], s[2:3]
	flat_load_dword v48, v[48:49] sc1
	s_mov_b64 s[18:19], 0
	s_waitcnt vmcnt(0) lgkmcnt(0)
	v_cmp_eq_u32_e32 vcc, 0, v48
	s_and_saveexec_b64 s[20:21], vcc
	s_cmp_lt_u32 s25, 0x100001
	s_cselect_b64 s[18:19], -1, 0
	s_xor_b64 s[16:17], exec, -1
	s_and_b64 s[18:19], s[18:19], exec
	s_or_b64 exec, exec, s[20:21]

; __device__ __forceinline__ unsigned xb_ld(unsigned* p)              { return __hip_atomic_load(p, __ATOMIC_RELAXED, __HIP_MEMORY_SCOPE_AGENT); }
; __device__ __forceinline__ unsigned xb_add(unsigned* p, unsigned v) { return __hip_atomic_fetch_add(p, v, __ATOMIC_RELAXED, __HIP_MEMORY_SCOPE_AGENT); }
; #define XB_SPIN(cond, bar) do { unsigned _sp = 0; while (cond) { __builtin_amdgcn_s_sleep(1); \
;     if ((++_sp & 255u) == 0u) { if (xb_ld(&(bar)[XB_TMO])) break; if (_sp > XB_SPIN_CAP) { atomicAdd(&(bar)[XB_TMO], 1u); break; } } } } while (0)
; __device__ __forceinline__ void grid_barrier(unsigned* bar, volatile LAS unsigned* st, int wid) {
;     ...
;                 const unsigned tg = og / nx;
;                 if (og + 1u == (tg + 1u) * nx) xb_add(&bar[XB_TOPGEN], 1u);
;                 else XB_SPIN(xb_ld(&bar[XB_TOPGEN]) == tg, bar);
;                 __builtin_amdgcn_fence(__ATOMIC_ACQUIRE, "agent");
;                 xb_add(&bar[XB_XGEN(x)], 1u);
;                 asm volatile("s_waitcnt vmcnt(0)" ::: "memory");
;             } else {
;                 XB_SPIN(xb_ld(&bar[XB_XGEN(x)]) == gen, bar);
;                 __builtin_amdgcn_fence(__ATOMIC_ACQUIRE, "agent");
;                 asm volatile("s_waitcnt vmcnt(0)" ::: "memory");
;             }
.LBB0_1079:
	s_and_b32 s0, s28, 0xff
	s_mov_b64 s[16:17], -1
	s_cmp_lg_u32 s0, 0
	s_mov_b64 s[18:19], -1
	s_cbranch_scc1 .LBB0_1083
	v_mov_b64_e32 v[2:3], s[6:7]
	flat_load_dword v0, v[2:3] sc1
	s_mov_b64 s[18:19], 0
	s_mov_b64 s[20:21], -1
	s_waitcnt vmcnt(0) lgkmcnt(0)
	v_cmp_eq_u32_e32 vcc, 0, v0
	s_and_saveexec_b64 s[24:25], vcc
	s_cmp_lt_u32 s28, 0x100001
	s_cselect_b64 s[18:19], -1, 0
	s_xor_b64 s[20:21], exec, -1
	s_and_b64 s[18:19], s[18:19], exec
	s_or_b64 exec, exec, s[24:25]

; __device__ __forceinline__ unsigned xb_ld(unsigned* p)              { return __hip_atomic_load(p, __ATOMIC_RELAXED, __HIP_MEMORY_SCOPE_AGENT); }
; __device__ __forceinline__ unsigned xb_add(unsigned* p, unsigned v) { return __hip_atomic_fetch_add(p, v, __ATOMIC_RELAXED, __HIP_MEMORY_SCOPE_AGENT); }
; #define XB_SPIN(cond, bar) do { unsigned _sp = 0; while (cond) { __builtin_amdgcn_s_sleep(1); \
;     if ((++_sp & 255u) == 0u) { if (xb_ld(&(bar)[XB_TMO])) break; if (_sp > XB_SPIN_CAP) { atomicAdd(&(bar)[XB_TMO], 1u); break; } } } } while (0)
; __device__ __forceinline__ void grid_barrier(unsigned* bar, volatile LAS unsigned* st, int wid) {
;     ...
;                 const unsigned tg = og / nx;
;                 if (og + 1u == (tg + 1u) * nx) xb_add(&bar[XB_TOPGEN], 1u);
;                 else XB_SPIN(xb_ld(&bar[XB_TOPGEN]) == tg, bar);
;                 __builtin_amdgcn_fence(__ATOMIC_ACQUIRE, "agent");
;                 xb_add(&bar[XB_XGEN(x)], 1u);
;                 asm volatile("s_waitcnt vmcnt(0)" ::: "memory");
;             } else {
;                 XB_SPIN(xb_ld(&bar[XB_XGEN(x)]) == gen, bar);
;                 __builtin_amdgcn_fence(__ATOMIC_ACQUIRE, "agent");
;                 asm volatile("s_waitcnt vmcnt(0)" ::: "memory");
;             }
.LBB0_1093:
	s_and_b32 s0, s23, 0xff
	s_cmp_lg_u32 s0, 0
	s_mov_b64 s[16:17], -1
	s_cbranch_scc1 .LBB0_1097
	v_mov_b64_e32 v[0:1], s[6:7]
	flat_load_dword v0, v[0:1] sc1
	s_mov_b64 s[16:17], 0
	s_mov_b64 s[14:15], -1
	s_waitcnt vmcnt(0) lgkmcnt(0)
	v_cmp_eq_u32_e32 vcc, 0, v0
	s_and_saveexec_b64 s[18:19], vcc
	s_cmp_lt_u32 s23, 0x100001
	s_cselect_b64 s[16:17], -1, 0
	s_xor_b64 s[14:15], exec, -1
	s_and_b64 s[16:17], s[16:17], exec
	s_or_b64 exec, exec, s[18:19]

; __device__ __forceinline__ unsigned xb_ld(unsigned* p)              { return __hip_atomic_load(p, __ATOMIC_RELAXED, __HIP_MEMORY_SCOPE_AGENT); }
; __device__ __forceinline__ void xcd_barrier_complete(unsigned* bar, unsigned x, unsigned& nloc, unsigned& nx) {
;     const unsigned G = gridDim.x * gridDim.y * gridDim.z;
;     unsigned sum, cnt, mine, sp = 0u;
;     for (;;) {
;         sum = 0u; cnt = 0u; mine = 0u;
; #pragma unroll
;         for (unsigned j = 0; j < 16; ++j) { const unsigned c = xb_ld(&bar[XB_XCNT(j)]); sum += c; cnt += (c > 0u) ? 1u : 0u; mine = (j == x) ? c : mine; }
;         if (sum == G) break;
;         __builtin_amdgcn_s_sleep(1);
;         if ((++sp & 255u) == 0u) { if (xb_ld(&bar[XB_TMO])) break; if (sp > XB_SPIN_CAP) { atomicAdd(&bar[XB_TMO], 1u); break; } }
;     }
;     nloc = mine > 0u ? mine : 1u; nx = cnt > 0u ? cnt : 1u;
; }
.LBB0_3262:
	flat_load_dword v47, v[0:1] sc1
	flat_load_dword v32, v[2:3] sc1
	flat_load_dword v33, v[4:5] sc1
	flat_load_dword v34, v[6:7] sc1
	flat_load_dword v35, v[8:9] sc1
	flat_load_dword v36, v[10:11] sc1
	flat_load_dword v37, v[12:13] sc1
	flat_load_dword v38, v[14:15] sc1
	flat_load_dword v39, v[16:17] sc1
	flat_load_dword v40, v[18:19] sc1
	flat_load_dword v41, v[20:21] sc1
	flat_load_dword v42, v[22:23] sc1
	flat_load_dword v43, v[24:25] sc1
	flat_load_dword v44, v[26:27] sc1
	flat_load_dword v45, v[28:29] sc1
	flat_load_dword v46, v[30:31] sc1
	s_or_b64 s[8:9], s[8:9], exec
	s_or_b64 s[6:7], s[6:7], exec
	s_waitcnt vmcnt(0) lgkmcnt(0)
	v_add_u32_e32 v48, v32, v47
	v_add_u32_e32 v48, v48, v33
	v_add_u32_e32 v48, v48, v34
	v_add_u32_e32 v48, v48, v35
	v_add_u32_e32 v48, v48, v36
	v_add_u32_e32 v48, v48, v37
	v_add_u32_e32 v48, v48, v38
	v_add_u32_e32 v48, v48, v39
	v_add_u32_e32 v48, v48, v40
	v_add_u32_e32 v48, v48, v41
	v_add_u32_e32 v48, v48, v42
	v_add_u32_e32 v48, v48, v43
	v_add_u32_e32 v48, v48, v44
	v_add_u32_e32 v48, v48, v45
	v_add_u32_e32 v48, v48, v46
	v_cmp_ne_u32_e32 vcc, s20, v48
	s_and_saveexec_b64 s[10:11], vcc
	s_cbranch_execz .LBB0_3261
	s_and_b32 s14, s21, 0xff
	s_mov_b64 s[12:13], -1
	s_cmp_eq_u32 s14, 0
	s_mov_b64 s[16:17], -1
	s_mov_b64 s[14:15], -1
	s_cbranch_scc0 .LBB0_3267
	v_mov_b64_e32 v[48:49], s[0:1]
	flat_load_dword v48, v[48:49] sc1
	s_mov_b64 s[16:17], 0
	s_waitcnt vmcnt(0) lgkmcnt(0)
	v_cmp_eq_u32_e32 vcc, 0, v48
	s_and_saveexec_b64 s[18:19], vcc
	s_cmp_lt_u32 s21, 0x100001
	s_cselect_b64 s[16:17], -1, 0
	s_xor_b64 s[14:15], exec, -1
	s_and_b64 s[16:17], s[16:17], exec
	s_or_b64 exec, exec, s[18:19]

; __device__ __forceinline__ unsigned xb_ld(unsigned* p)              { return __hip_atomic_load(p, __ATOMIC_RELAXED, __HIP_MEMORY_SCOPE_AGENT); }
; __device__ __forceinline__ unsigned xb_add(unsigned* p, unsigned v) { return __hip_atomic_fetch_add(p, v, __ATOMIC_RELAXED, __HIP_MEMORY_SCOPE_AGENT); }
; #define XB_SPIN(cond, bar) do { unsigned _sp = 0; while (cond) { __builtin_amdgcn_s_sleep(1); \
;     if ((++_sp & 255u) == 0u) { if (xb_ld(&(bar)[XB_TMO])) break; if (_sp > XB_SPIN_CAP) { atomicAdd(&(bar)[XB_TMO], 1u); break; } } } } while (0)
; __device__ __forceinline__ void grid_barrier(unsigned* bar, volatile LAS unsigned* st, int wid) {
;     ...
;                 const unsigned tg = og / nx;
;                 if (og + 1u == (tg + 1u) * nx) xb_add(&bar[XB_TOPGEN], 1u);
;                 else XB_SPIN(xb_ld(&bar[XB_TOPGEN]) == tg, bar);
;                 __builtin_amdgcn_fence(__ATOMIC_ACQUIRE, "agent");
;                 xb_add(&bar[XB_XGEN(x)], 1u);
;                 asm volatile("s_waitcnt vmcnt(0)" ::: "memory");
;             } else {
;                 XB_SPIN(xb_ld(&bar[XB_XGEN(x)]) == gen, bar);
;                 __builtin_amdgcn_fence(__ATOMIC_ACQUIRE, "agent");
;                 asm volatile("s_waitcnt vmcnt(0)" ::: "memory");
;             }
.LBB0_3276:
	s_and_b32 s16, s24, 0xff
	s_mov_b64 s[14:15], -1
	s_cmp_lg_u32 s16, 0
	s_mov_b64 s[16:17], -1
	s_cbranch_scc1 .LBB0_3280
	v_mov_b64_e32 v[2:3], s[4:5]
	flat_load_dword v0, v[2:3] sc1
	s_mov_b64 s[16:17], 0
	s_mov_b64 s[18:19], -1
	s_waitcnt vmcnt(0) lgkmcnt(0)
	v_cmp_eq_u32_e32 vcc, 0, v0
	s_and_saveexec_b64 s[20:21], vcc
	s_cmp_lt_u32 s24, 0x100001
	s_cselect_b64 s[16:17], -1, 0
	s_xor_b64 s[18:19], exec, -1
	s_and_b64 s[16:17], s[16:17], exec
	s_or_b64 exec, exec, s[20:21]

; __device__ __forceinline__ unsigned xb_ld(unsigned* p)              { return __hip_atomic_load(p, __ATOMIC_RELAXED, __HIP_MEMORY_SCOPE_AGENT); }
; __device__ __forceinline__ unsigned xb_add(unsigned* p, unsigned v) { return __hip_atomic_fetch_add(p, v, __ATOMIC_RELAXED, __HIP_MEMORY_SCOPE_AGENT); }
; #define XB_SPIN(cond, bar) do { unsigned _sp = 0; while (cond) { __builtin_amdgcn_s_sleep(1); \
;     if ((++_sp & 255u) == 0u) { if (xb_ld(&(bar)[XB_TMO])) break; if (_sp > XB_SPIN_CAP) { atomicAdd(&(bar)[XB_TMO], 1u); break; } } } } while (0)
; __device__ __forceinline__ void grid_barrier(unsigned* bar, volatile LAS unsigned* st, int wid) {
;     ...
;                 const unsigned tg = og / nx;
;                 if (og + 1u == (tg + 1u) * nx) xb_add(&bar[XB_TOPGEN], 1u);
;                 else XB_SPIN(xb_ld(&bar[XB_TOPGEN]) == tg, bar);
;                 __builtin_amdgcn_fence(__ATOMIC_ACQUIRE, "agent");
;                 xb_add(&bar[XB_XGEN(x)], 1u);
;                 asm volatile("s_waitcnt vmcnt(0)" ::: "memory");
;             } else {
;                 XB_SPIN(xb_ld(&bar[XB_XGEN(x)]) == gen, bar);
;                 __builtin_amdgcn_fence(__ATOMIC_ACQUIRE, "agent");
;                 asm volatile("s_waitcnt vmcnt(0)" ::: "memory");
;             }
.LBB0_3290:
	s_and_b32 s12, s20, 0xff
	s_cmp_lg_u32 s12, 0
	s_mov_b64 s[14:15], -1
	s_cbranch_scc1 .LBB0_3294
	v_mov_b64_e32 v[0:1], s[4:5]
	flat_load_dword v0, v[0:1] sc1
	s_mov_b64 s[14:15], 0
	s_mov_b64 s[12:13], -1
	s_waitcnt vmcnt(0) lgkmcnt(0)
	v_cmp_eq_u32_e32 vcc, 0, v0
	s_and_saveexec_b64 s[16:17], vcc
	s_cmp_lt_u32 s20, 0x100001
	s_cselect_b64 s[14:15], -1, 0
	s_xor_b64 s[12:13], exec, -1
	s_and_b64 s[14:15], s[14:15], exec
	s_or_b64 exec, exec, s[16:17]
